# gdn chain: q@S/k@S fragment reads ring-scheduled and the chunk-output section (attention@v_new MFMAs, fma/convert/store) rescheduled with all fragment reads up front
# baseline (speedup 1.0000x reference)
; #define LAS __attribute__((address_space(3)))
; __device__ __forceinline__ unsigned pk2(float lo, float hi) { const f32v2_t f = {lo, hi}; const bf16v2_t b = __builtin_convertvector(f, bf16v2_t); return __builtin_bit_cast(unsigned, b); }
; #define WAVE_SYNC() do { asm volatile("s_waitcnt lgkmcnt(0)" ::: "memory"); __builtin_amdgcn_wave_barrier(); asm volatile("" ::: "memory"); } while (0)
; #define MFMA16(a, b, c) __builtin_amdgcn_mfma_f32_16x16x32_bf16((a), (b), (c), 0, 0, 0)
; template <int MODE>
; __device__ NOINL void chain_item(const LAS Params* lp, int l, int item, bool ctx_out, LAS unsigned char* lds) {
;     ...
;         for (int dk = 0; dk < NDK; ++dk) { u32x2 pk; pk.x = pk2(Sacc[dk][0], Sacc[dk][1]); pk.y = pk2(Sacc[dk][2], Sacc[dk][3]); *(LAS u32x2*)(ST + fr * 136 + 16 * dk + 4 * fq) = pk; }
;         WAVE_SYNC();
;         f32x4 qs[4], ksm[4];
; #pragma unroll
;         for (int ct = 0; ct < 4; ++ct) { qs[ct] = (f32x4){0.f, 0.f, 0.f, 0.f}; ksm[ct] = (f32x4){0.f, 0.f, 0.f, 0.f}; }
; #pragma unroll
;         for (int ks = 0; ks < NKS; ++ks) {
;             const bf16x8 Bf = *(const LAS bf16x8*)(ST + fr * 136 + ks * 32 + fq * 8);
; #pragma unroll
;             for (int ct = 0; ct < 4; ++ct) {
;                 const bf16x8 Aq = *(const LAS bf16x8*)(Qs + (16 * ct + fr) * 136 + kcol + ks * 32 + fq * 8);
;                 qs[ct] = MFMA16(Aq, Bf, qs[ct]);
;                 if (MODE == 0) { const bf16x8 Ak = *(const LAS bf16x8*)(Ks + (16 * ct + fr) * 136 + ks * 32 + fq * 8); ksm[ct] = MFMA16(Ak, Bf, ksm[ct]); }
;             }
;         }
.LBB0_1141:
	s_or_b64 exec, exec, s[62:63]
	ds_write_b16 v178, v68
	v_cvt_pk_bf16_f32 v68, v28, v29
	v_cvt_pk_bf16_f32 v69, v30, v31
	v_cvt_pk_bf16_f32 v70, v40, v41
	v_cvt_pk_bf16_f32 v71, v42, v43
	s_waitcnt lgkmcnt(0)
	s_barrier
	ds_write2_b64 v113, v[68:69], v[70:71] offset1:4
	v_cvt_pk_bf16_f32 v68, v32, v33
	v_cvt_pk_bf16_f32 v69, v34, v35
	v_cvt_pk_bf16_f32 v70, v36, v37
	v_cvt_pk_bf16_f32 v71, v38, v39
	ds_write2_b64 v113, v[68:69], v[70:71] offset0:8 offset1:12
	v_cvt_pk_bf16_f32 v68, v56, v57
	v_cvt_pk_bf16_f32 v69, v58, v59
	v_cvt_pk_bf16_f32 v70, v52, v53
	v_cvt_pk_bf16_f32 v71, v54, v55
	ds_write2_b64 v113, v[68:69], v[70:71] offset0:16 offset1:20
	v_cvt_pk_bf16_f32 v68, v44, v45
	v_cvt_pk_bf16_f32 v69, v46, v47
	v_cvt_pk_bf16_f32 v70, v48, v49
	v_cvt_pk_bf16_f32 v71, v50, v51
	ds_write2_b64 v113, v[68:69], v[70:71] offset0:24 offset1:28
	s_waitcnt lgkmcnt(0)
	v_add_u32_e32 v119, v113, v154
	ds_read_b128 v[84:87], v119
	ds_read_b128 v[100:103], v179
	ds_read_b128 v[104:107], v179 offset:17408
	ds_read_b128 v[194:197], v179 offset:4352
	ds_read_b128 v[236:239], v179 offset:21760
	ds_read_b128 v[240:243], v179 offset:8704
	ds_read_b128 v[244:247], v179 offset:26112
	ds_read_b128 v[248:251], v179 offset:13056
	v_add_u32_e32 v121, 0x25500, v110
	s_waitcnt lgkmcnt(6)
	v_mfma_f32_16x16x32_bf16 v[96:99], v[100:103], v[84:87], 0
	ds_read_b128 v[100:103], v179 offset:30464
	ds_read_b128 v[88:91], v119 offset:64
	s_add_i32 s5, s4, 4
	s_waitcnt lgkmcnt(7)
	v_mfma_f32_16x16x32_bf16 v[198:201], v[104:107], v[84:87], 0
	ds_read_b128 v[104:107], v179 offset:64
	s_and_b64 s[20:21], vcc, exec
	s_waitcnt lgkmcnt(7)
	v_mfma_f32_16x16x32_bf16 v[92:95], v[194:197], v[84:87], 0
	ds_read_b128 v[194:197], v179 offset:17472
	s_cselect_b32 s5, s1, s5
	s_waitcnt lgkmcnt(7)
	v_mfma_f32_16x16x32_bf16 v[232:235], v[236:239], v[84:87], 0
	ds_read_b128 v[236:239], v179 offset:4416
	s_add_i32 s22, s4, 40
	s_waitcnt lgkmcnt(7)
	v_mfma_f32_16x16x32_bf16 v[80:83], v[240:243], v[84:87], 0
	ds_read_b128 v[240:243], v179 offset:21824
	s_and_b64 s[20:21], vcc, exec
	s_waitcnt lgkmcnt(7)
	v_mfma_f32_16x16x32_bf16 v[72:75], v[244:247], v[84:87], 0
	ds_read_b128 v[244:247], v179 offset:8768
	s_cselect_b32 s20, s1, s22
	s_waitcnt lgkmcnt(7)
	v_mfma_f32_16x16x32_bf16 v[76:79], v[248:251], v[84:87], 0
	ds_read_b128 v[248:251], v179 offset:26176
	s_cmp_lt_u32 s1, 4
	s_waitcnt lgkmcnt(7)
	v_mfma_f32_16x16x32_bf16 v[68:71], v[100:103], v[84:87], 0
	ds_read_b128 v[100:103], v179 offset:13120
	s_cselect_b32 s1, s5, s20
	s_waitcnt lgkmcnt(6)
	v_mfma_f32_16x16x32_bf16 v[96:99], v[104:107], v[88:91], v[96:99]
	ds_read_b128 v[104:107], v179 offset:30528
	ds_read_b128 v[84:87], v119 offset:128
	s_lshl_b32 s5, s1, 6
	s_waitcnt lgkmcnt(7)
	v_mfma_f32_16x16x32_bf16 v[198:201], v[194:197], v[88:91], v[198:201]
	ds_read_b128 v[194:197], v179 offset:128
	s_add_i32 s20, s18, s5
	s_waitcnt lgkmcnt(7)
	v_mfma_f32_16x16x32_bf16 v[92:95], v[236:239], v[88:91], v[92:95]
	ds_read_b128 v[236:239], v179 offset:17536
	s_or_b32 s5, s5, s38
	s_waitcnt lgkmcnt(7)
	v_mfma_f32_16x16x32_bf16 v[232:235], v[240:243], v[88:91], v[232:235]
	ds_read_b128 v[240:243], v179 offset:4480
	s_cmp_lt_u32 s1, 4
	s_waitcnt lgkmcnt(7)
	v_mfma_f32_16x16x32_bf16 v[80:83], v[244:247], v[88:91], v[80:83]
	ds_read_b128 v[244:247], v179 offset:21888
	s_cselect_b32 s1, s5, s20
	s_waitcnt lgkmcnt(7)
	v_mfma_f32_16x16x32_bf16 v[72:75], v[248:251], v[88:91], v[72:75]
	ds_read_b128 v[248:251], v179 offset:8832
	s_mul_hi_i32 s21, s1, s19
	s_waitcnt lgkmcnt(7)
	v_mfma_f32_16x16x32_bf16 v[76:79], v[100:103], v[88:91], v[76:79]
	ds_read_b128 v[100:103], v179 offset:26240
	s_mul_i32 s20, s1, s19
	s_waitcnt lgkmcnt(7)
	v_mfma_f32_16x16x32_bf16 v[68:71], v[104:107], v[88:91], v[68:71]
	ds_read_b128 v[104:107], v179 offset:13184
	v_mov_b32_e32 v123, v1
	s_waitcnt lgkmcnt(6)
	v_mfma_f32_16x16x32_bf16 v[96:99], v[194:197], v[84:87], v[96:99]
	ds_read_b128 v[194:197], v179 offset:30592
	ds_read_b128 v[88:91], v119 offset:192
	v_add_u32_e32 v119, s34, v155
	v_mov_b32_e32 v125, v1
	s_waitcnt lgkmcnt(7)
	v_mfma_f32_16x16x32_bf16 v[198:201], v[236:239], v[84:87], v[198:201]
	ds_read_b128 v[236:239], v179 offset:192
	v_mov_b32_e32 v127, v1
	s_waitcnt lgkmcnt(7)
	v_mfma_f32_16x16x32_bf16 v[92:95], v[240:243], v[84:87], v[92:95]
	ds_read_b128 v[240:243], v179 offset:17600
	v_mov_b32_e32 v129, v1
	s_waitcnt lgkmcnt(7)
	v_mfma_f32_16x16x32_bf16 v[232:235], v[244:247], v[84:87], v[232:235]
	ds_read_b128 v[244:247], v179 offset:4544
	v_mov_b32_e32 v131, v1
	s_waitcnt lgkmcnt(7)
	v_mfma_f32_16x16x32_bf16 v[80:83], v[248:251], v[84:87], v[80:83]
	ds_read_b128 v[248:251], v179 offset:21952
	v_mov_b32_e32 v133, v1
	s_waitcnt lgkmcnt(7)
	v_mfma_f32_16x16x32_bf16 v[72:75], v[100:103], v[84:87], v[72:75]
	ds_read_b128 v[100:103], v179 offset:8896
	v_mov_b32_e32 v135, v1
	s_waitcnt lgkmcnt(7)
	v_mfma_f32_16x16x32_bf16 v[76:79], v[104:107], v[84:87], v[76:79]
	ds_read_b128 v[104:107], v179 offset:26304
	v_mov_b32_e32 v137, v1
	s_waitcnt lgkmcnt(7)
	v_mfma_f32_16x16x32_bf16 v[68:71], v[194:197], v[84:87], v[68:71]
	ds_read_b128 v[194:197], v179 offset:13248
	v_mov_b32_e32 v139, v1
	s_waitcnt lgkmcnt(6)
	v_mfma_f32_16x16x32_bf16 v[96:99], v[236:239], v[88:91], v[96:99]
	ds_read_b128 v[236:239], v179 offset:30656
	v_mov_b32_e32 v141, v1
	s_waitcnt lgkmcnt(6)
	v_mfma_f32_16x16x32_bf16 v[198:201], v[240:243], v[88:91], v[198:201]
	v_mov_b32_e32 v143, v1
	s_waitcnt lgkmcnt(5)
	v_mfma_f32_16x16x32_bf16 v[92:95], v[244:247], v[88:91], v[92:95]
	v_mov_b32_e32 v145, v1
	s_waitcnt lgkmcnt(4)
	v_mfma_f32_16x16x32_bf16 v[232:235], v[248:251], v[88:91], v[232:235]
	v_mov_b32_e32 v147, v1
	s_waitcnt lgkmcnt(3)
; #define LAS __attribute__((address_space(3)))
; template <int MODE>
; __device__ NOINL void chain_item(const LAS Params* lp, int l, int item, bool ctx_out, LAS unsigned char* lds) {
;     ...
;         float eg[4][4];
; #pragma unroll
;         for (int ct = 0; ct < 4; ++ct)
; #pragma unroll
;             for (int j = 0; j < 4; ++j) { const int c = 16 * ct + 4 * fq + j; eg[ct][j] = MODE == 0 ? gcs[128 + c] : __expf((float)(c + 1) * lg); }
;         bf16x8 Bv[2];
;         if (MODE == 0) {
; #pragma unroll
;             for (int ct = 0; ct < 4; ++ct) {
;                 const u32x2 vv = *(const LAS u32x2*)(VT + (dvrow + fr) * 72 + (((2 * ct + (fq >> 1)) ^ vkey) << 3) + 4 * (fq & 1));
;                 const float v4[4] = {bflo(vv.x), bfhi(vv.x), bflo(vv.y), bfhi(vv.y)};
;                 float r[4];
; #pragma unroll
;                 for (int j = 0; j < 4; ++j) r[j] = bts[16 * ct + 4 * fq + j] * (v4[j] - eg[ct][j] * ksm[ct][j]);
;                 u32x2 pk; pk.x = pk2(r[0], r[1]); pk.y = pk2(r[2], r[3]);
;                 *(LAS u32x2*)(RP + fr * 72 + 16 * ct + 4 * fq) = pk;
;             }
;             WAVE_SYNC();
;             bf16x8 Br[2];
;             Br[0] = *(const LAS bf16x8*)(RP + fr * 72 + fq * 8); Br[1] = *(const LAS bf16x8*)(RP + fr * 72 + 32 + fq * 8);
;             f32x4 vn[4];
; #pragma unroll
;             for (int ct = 0; ct < 4; ++ct) {
;                 vn[ct] = (f32x4){0.f, 0.f, 0.f, 0.f};
; #pragma unroll
;                 for (int ks = 0; ks < 2; ++ks) { const bf16x8 A = *(const LAS bf16x8*)(TT + (16 * ct + fr) * 72 + ks * 32 + fq * 8); vn[ct] = MFMA16(A, Br[ks], vn[ct]); }
;             }
;             WAVE_SYNC();
; #pragma unroll
;             for (int ct = 0; ct < 4; ++ct) { u32x2 pk; pk.x = pk2(vn[ct][0], vn[ct][1]); pk.y = pk2(vn[ct][2], vn[ct][3]); *(LAS u32x2*)(RP + fr * 72 + 16 * ct + 4 * fq) = pk; }
;             WAVE_SYNC();
;             Bv[0] = *(const LAS bf16x8*)(RP + fr * 72 + fq * 8); Bv[1] = *(const LAS bf16x8*)(RP + fr * 72 + 32 + fq * 8);
;         } else {
;             Bv[0] = *(const LAS bf16x8*)(VT + (dvrow + fr) * 72 + ((fq ^ vkey) << 3)); Bv[1] = *(const LAS bf16x8*)(VT + (dvrow + fr) * 72 + (((4 + fq) ^ vkey) << 3));
;         }
;         {
;             typedef __attribute__((address_space(1))) bf16_t gbf16;
;             bf16_t* ob; int ldo;
	v_mfma_f32_16x16x32_bf16 v[80:83], v[100:103], v[88:91], v[80:83]
	s_add_i32 s4, s4, -1
	s_waitcnt lgkmcnt(2)
	v_mfma_f32_16x16x32_bf16 v[72:75], v[104:107], v[88:91], v[72:75]
	s_cmp_lg_u32 s0, 36
	s_waitcnt lgkmcnt(1)
	v_mfma_f32_16x16x32_bf16 v[76:79], v[194:197], v[88:91], v[76:79]
	s_mov_b32 s1, s0
	s_waitcnt lgkmcnt(0)
	v_mfma_f32_16x16x32_bf16 v[68:71], v[236:239], v[88:91], v[68:71]
	ds_read_b64 v[88:89], v186 offset:53248
	ds_read_b128 v[104:107], v119 offset:512
	ds_read_b128 v[84:87], v121
	s_waitcnt lgkmcnt(2)
	v_lshlrev_b32_e32 v90, 16, v88
	v_and_b32_e32 v91, 0xffff0000, v88
	v_lshlrev_b32_e32 v88, 16, v89
	v_and_b32_e32 v89, 0xffff0000, v89
	s_waitcnt lgkmcnt(1)
	v_pk_fma_f32 v[90:91], v[198:199], v[104:105], v[90:91] neg_lo:[1,0,0] neg_hi:[1,0,0]
	v_pk_fma_f32 v[88:89], v[200:201], v[106:107], v[88:89] neg_lo:[1,0,0] neg_hi:[1,0,0]
	s_waitcnt lgkmcnt(0)
	v_pk_mul_f32 v[84:85], v[84:85], v[90:91]
	v_pk_mul_f32 v[86:87], v[86:87], v[88:89]
	v_cvt_pk_bf16_f32 v148, v84, v85
	v_cvt_pk_bf16_f32 v149, v86, v87
	ds_read_b128 v[100:103], v119 offset:576
	ds_read_b128 v[88:91], v119 offset:640
	ds_read_b128 v[84:87], v119 offset:704
	ds_write_b64 v158, v[148:149] offset:4352
	ds_read_b64 v[148:149], v187 offset:53248
	ds_read_b128 v[194:197], v121 offset:64
	v_add_u32_e32 v119, v158, v154
	s_waitcnt lgkmcnt(1)
	v_lshlrev_b32_e32 v198, 16, v148
	v_and_b32_e32 v199, 0xffff0000, v148
	v_lshlrev_b32_e32 v148, 16, v149
	v_and_b32_e32 v149, 0xffff0000, v149
	v_pk_fma_f32 v[198:199], v[232:233], v[100:101], v[198:199] neg_lo:[1,0,0] neg_hi:[1,0,0]
	v_pk_fma_f32 v[148:149], v[234:235], v[102:103], v[148:149] neg_lo:[1,0,0] neg_hi:[1,0,0]
	s_waitcnt lgkmcnt(0)
	v_pk_mul_f32 v[194:195], v[194:195], v[198:199]
	v_pk_mul_f32 v[148:149], v[196:197], v[148:149]
	v_cvt_pk_bf16_f32 v194, v194, v195
	v_cvt_pk_bf16_f32 v195, v148, v149
	ds_write_b64 v158, v[194:195] offset:4384
	ds_read_b64 v[148:149], v188 offset:53248
	ds_read_b128 v[194:197], v121 offset:128
	s_waitcnt lgkmcnt(1)
	v_lshlrev_b32_e32 v198, 16, v148
	v_and_b32_e32 v199, 0xffff0000, v148
	v_lshlrev_b32_e32 v148, 16, v149
	v_and_b32_e32 v149, 0xffff0000, v149
	v_pk_fma_f32 v[72:73], v[72:73], v[88:89], v[198:199] neg_lo:[1,0,0] neg_hi:[1,0,0]
	v_pk_fma_f32 v[74:75], v[74:75], v[90:91], v[148:149] neg_lo:[1,0,0] neg_hi:[1,0,0]
	s_waitcnt lgkmcnt(0)
	v_pk_mul_f32 v[72:73], v[194:195], v[72:73]
	v_pk_mul_f32 v[74:75], v[196:197], v[74:75]
	v_cvt_pk_bf16_f32 v72, v72, v73
	v_cvt_pk_bf16_f32 v73, v74, v75
	ds_write_b64 v158, v[72:73] offset:4416
	ds_read_b64 v[72:73], v189 offset:53248
	s_waitcnt lgkmcnt(0)
	v_lshlrev_b32_e32 v148, 16, v72
	v_and_b32_e32 v149, 0xffff0000, v72
	v_lshlrev_b32_e32 v194, 16, v73
	v_and_b32_e32 v195, 0xffff0000, v73
	ds_read_b128 v[72:75], v121 offset:192
	v_pk_fma_f32 v[68:69], v[68:69], v[84:85], v[148:149] neg_lo:[1,0,0] neg_hi:[1,0,0]
	v_pk_fma_f32 v[70:71], v[70:71], v[86:87], v[194:195] neg_lo:[1,0,0] neg_hi:[1,0,0]
	v_add_u32_e32 v121, v159, v157
	v_lshl_add_u64 v[148:149], s[20:21], 1, v[116:117]
	s_waitcnt lgkmcnt(0)
	v_pk_mul_f32 v[68:69], v[72:73], v[68:69]
	v_pk_mul_f32 v[70:71], v[74:75], v[70:71]
	v_cvt_pk_bf16_f32 v68, v68, v69
	v_cvt_pk_bf16_f32 v69, v70, v71
	ds_write_b64 v158, v[68:69] offset:4448
	s_waitcnt lgkmcnt(0)
	ds_read_b128 v[68:71], v119 offset:4352
	ds_read_b128 v[72:75], v119 offset:4416
	ds_read_b128 v[194:197], v121
	ds_read_b128 v[198:201], v121 offset:64
	s_waitcnt lgkmcnt(1)
	v_mfma_f32_16x16x32_bf16 v[194:197], v[194:197], v[68:71], 0
	v_add_u32_e32 v121, v159, v180
	ds_read_b128 v[232:235], v121 offset:64
	ds_read_b128 v[236:239], v121 offset:2368
	s_waitcnt lgkmcnt(2)
	v_mfma_f32_16x16x32_bf16 v[194:197], v[198:201], v[72:75], v[194:197]
	ds_read_b128 v[198:201], v121
	s_waitcnt lgkmcnt(0)
	v_mfma_f32_16x16x32_bf16 v[198:201], v[198:201], v[68:71], 0
	v_mfma_f32_16x16x32_bf16 v[198:201], v[232:235], v[72:75], v[198:201]
	ds_read_b128 v[232:235], v121 offset:2304
	s_waitcnt lgkmcnt(0)
	v_mfma_f32_16x16x32_bf16 v[232:235], v[232:235], v[68:71], 0
	v_mfma_f32_16x16x32_bf16 v[232:235], v[236:239], v[72:75], v[232:235]
	ds_read_b128 v[236:239], v121 offset:4608
	s_waitcnt lgkmcnt(0)
	v_mfma_f32_16x16x32_bf16 v[68:71], v[236:239], v[68:71], 0
	ds_read_b128 v[236:239], v121 offset:4672
	v_add_u32_e32 v121, 0x1000, v158
	s_waitcnt lgkmcnt(0)
	s_waitcnt lgkmcnt(0)
	v_mfma_f32_16x16x32_bf16 v[68:71], v[236:239], v[72:75], v[68:71]
	v_cvt_pk_bf16_f32 v72, v194, v195
	v_cvt_pk_bf16_f32 v73, v196, v197
	v_cvt_pk_bf16_f32 v74, v198, v199
	v_cvt_pk_bf16_f32 v75, v200, v201
	ds_write2_b64 v121, v[72:73], v[74:75] offset0:32 offset1:36
	v_cvt_pk_bf16_f32 v72, v232, v233
	v_cvt_pk_bf16_f32 v73, v234, v235
	s_nop 0
	v_cvt_pk_bf16_f32 v68, v68, v69
	v_cvt_pk_bf16_f32 v69, v70, v71
	ds_write2_b64 v121, v[72:73], v[68:69] offset0:40 offset1:44
	s_waitcnt lgkmcnt(0)
	ds_read_b128 v[72:75], v119 offset:4352
	ds_read_b128 v[68:71], v119 offset:4416
	v_add_u32_e32 v218, v160, v157
	v_add_u32_e32 v219, v160, v180
	v_mov_b32_e32 v119, v1
	v_mov_b32_e32 v121, v1
	ds_read_b128 v[194:197], v218
	ds_read_b128 v[232:235], v219
	ds_read_b128 v[244:247], v219 offset:2304
	ds_read_b128 v[236:239], v219 offset:4608
	ds_read_b128 v[198:201], v218 offset:64
	ds_read_b128 v[240:243], v219 offset:64
	ds_read_b128 v[248:251], v219 offset:2368
	s_waitcnt lgkmcnt(6)
	v_mfma_f32_16x16x32_bf16 v[194:197], v[194:197], v[72:75], 0
	s_waitcnt lgkmcnt(5)
	v_mfma_f32_16x16x32_bf16 v[232:235], v[232:235], v[72:75], 0
	s_waitcnt lgkmcnt(4)
	v_mfma_f32_16x16x32_bf16 v[244:247], v[244:247], v[72:75], 0
	s_waitcnt lgkmcnt(3)
	v_mfma_f32_16x16x32_bf16 v[236:239], v[236:239], v[72:75], 0
	s_waitcnt lgkmcnt(2)
; #define LAS __attribute__((address_space(3)))
; __device__ __forceinline__ bf16_t f2bf(float f) { return (bf16_t)(pk2(f, f) & 0xFFFFu); }
; #define MFMA16(a, b, c) __builtin_amdgcn_mfma_f32_16x16x32_bf16((a), (b), (c), 0, 0, 0)
; template <int MODE>
; __device__ NOINL void chain_item(const LAS Params* lp, int l, int item, bool ctx_out, LAS unsigned char* lds) {
;     ...
;         {
;             typedef __attribute__((address_space(1))) bf16_t gbf16;
;             bf16_t* ob; int ldo;
;             if (MODE == 0) { if (dir == 0) { ob = p.hbuf + 256 + h * 128 + 16 * w; ldo = 1024; } else { ob = p.hyproj + h * 128 + 16 * w; ldo = 768; } }
;             else { if (dir == 0) { ob = p.hbuf + 768 + (h + hh) * 64 + 16 * (w & 3); ldo = 1024; } else { ob = p.hyproj + 512 + (h + hh) * 64 + 16 * (w & 3); ldo = 768; } }
; #pragma unroll
;             for (int ct = 0; ct < 4; ++ct) {
;                 f32x4 acc = {0.f, 0.f, 0.f, 0.f};
; #pragma unroll
;                 for (int ks = 0; ks < 2; ++ks) { const bf16x8 A = *(const LAS bf16x8*)(AT + hh * 4608 + (16 * ct + fr) * 72 + ks * 32 + fq * 8); acc = MFMA16(A, Bv[ks], acc); }
;                 gbf16* og = (gbf16*)ob + (size_t)row0 * ldo + fr;
; #pragma unroll
;                 for (int j = 0; j < 4; ++j) { const int c = 16 * ct + 4 * fq + j, tok = dir ? 63 - c : c; og[tok * ldo] = f2bf(eg[ct][j] * qs[ct][j] + acc[j]); }
;             }
;         }
;         {
;             const float gl = MODE == 0 ? gcs[128 + 63] : __expf(64.f * lg);
; #pragma unroll
;             for (int dk = 0; dk < NDK; ++dk) {
;                 Sacc[dk] = Sacc[dk] * gl;
; #pragma unroll
;                 for (int ks = 0; ks < 2; ++ks) { const bf16x8 A = *(const LAS bf16x8*)(KT + (kcol + 16 * dk + fr) * 72 + (((ks * 4 + fq) ^ (((kcol >> 4) + dk) & 7)) << 3)); Sacc[dk] = MFMA16(A, Bv[ks], Sacc[dk]); }
;             }
	v_mfma_f32_16x16x32_bf16 v[194:197], v[198:201], v[68:71], v[194:197]
	ds_read_b128 v[198:201], v219 offset:4672
	s_waitcnt lgkmcnt(2)
	v_mfma_f32_16x16x32_bf16 v[232:235], v[240:243], v[68:71], v[232:235]
	s_waitcnt lgkmcnt(1)
	v_mfma_f32_16x16x32_bf16 v[244:247], v[248:251], v[68:71], v[244:247]
	s_waitcnt lgkmcnt(0)
	v_mfma_f32_16x16x32_bf16 v[236:239], v[198:201], v[68:71], v[236:239]
	v_lshl_add_u64 v[240:241], v[148:149], 0, v[0:1]
	v_lshl_add_u64 v[242:243], v[148:149], 0, v[118:119]
	v_lshl_add_u64 v[248:249], v[148:149], 0, v[120:121]
	v_lshl_add_u64 v[250:251], v[148:149], 0, v[122:123]
	s_nop 3
	v_fma_f32 v194, v96, v104, v194
	v_fma_f32 v195, v97, v105, v195
	v_fma_f32 v196, v98, v106, v196
	v_fma_f32 v197, v99, v107, v197
	v_cvt_pk_bf16_f32 v194, v194, v194
	v_cvt_pk_bf16_f32 v195, v195, v195
	v_cvt_pk_bf16_f32 v196, v196, v196
	v_cvt_pk_bf16_f32 v197, v197, v197
	global_store_short v[240:241], v194, off
	global_store_short v[242:243], v195, off
	global_store_short v[248:249], v196, off
	global_store_short v[250:251], v197, off
	v_lshl_add_u64 v[240:241], v[148:149], 0, v[124:125]
	v_lshl_add_u64 v[242:243], v[148:149], 0, v[126:127]
	v_lshl_add_u64 v[248:249], v[148:149], 0, v[128:129]
	v_lshl_add_u64 v[250:251], v[148:149], 0, v[130:131]
	v_fma_f32 v232, v92, v100, v232
	v_fma_f32 v233, v93, v101, v233
	v_fma_f32 v234, v94, v102, v234
	v_fma_f32 v235, v95, v103, v235
	v_cvt_pk_bf16_f32 v232, v232, v232
	v_cvt_pk_bf16_f32 v233, v233, v233
	v_cvt_pk_bf16_f32 v234, v234, v234
	v_cvt_pk_bf16_f32 v235, v235, v235
	global_store_short v[240:241], v232, off
	global_store_short v[242:243], v233, off
	global_store_short v[248:249], v234, off
	global_store_short v[250:251], v235, off
	v_lshl_add_u64 v[240:241], v[148:149], 0, v[132:133]
	v_lshl_add_u64 v[242:243], v[148:149], 0, v[134:135]
	v_lshl_add_u64 v[248:249], v[148:149], 0, v[136:137]
	v_lshl_add_u64 v[250:251], v[148:149], 0, v[138:139]
	v_fma_f32 v244, v80, v88, v244
	v_fma_f32 v245, v81, v89, v245
	v_fma_f32 v246, v82, v90, v246
	v_fma_f32 v247, v83, v91, v247
	v_cvt_pk_bf16_f32 v244, v244, v244
	v_cvt_pk_bf16_f32 v245, v245, v245
	v_cvt_pk_bf16_f32 v246, v246, v246
	v_cvt_pk_bf16_f32 v247, v247, v247
	global_store_short v[240:241], v244, off
	global_store_short v[242:243], v245, off
	global_store_short v[248:249], v246, off
	global_store_short v[250:251], v247, off
	v_lshl_add_u64 v[240:241], v[148:149], 0, v[140:141]
	v_lshl_add_u64 v[242:243], v[148:149], 0, v[142:143]
	v_lshl_add_u64 v[248:249], v[148:149], 0, v[144:145]
	v_lshl_add_u64 v[250:251], v[148:149], 0, v[146:147]
	v_fma_f32 v236, v76, v84, v236
	v_fma_f32 v237, v77, v85, v237
	v_fma_f32 v238, v78, v86, v238
	v_fma_f32 v239, v79, v87, v239
	v_cvt_pk_bf16_f32 v236, v236, v236
	v_cvt_pk_bf16_f32 v237, v237, v237
	v_cvt_pk_bf16_f32 v238, v238, v238
	v_cvt_pk_bf16_f32 v239, v239, v239
	global_store_short v[240:241], v236, off
	global_store_short v[242:243], v237, off
	global_store_short v[248:249], v238, off
	global_store_short v[250:251], v239, off
	v_mov_b32_e32 v76, s17
	ds_read_b32 v76, v76
	v_add_u32_e32 v83, v161, v155
	v_add_u32_e32 v82, v181, v182
	v_add_u32_e32 v84, v161, v182
	v_add_u32_e32 v85, v161, v183
	v_add_u32_e32 v86, v161, v162
	ds_read_b128 v[88:91], v83 offset:34816
	ds_read_b128 v[92:95], v82 offset:34816
	ds_read_b128 v[96:99], v190 offset:34816
	ds_read_b128 v[100:103], v191 offset:34816
	ds_read_b128 v[104:107], v83 offset:44096
	ds_read_b128 v[194:197], v84 offset:46400
	ds_read_b128 v[198:201], v85 offset:48704
	ds_read_b128 v[232:235], v86 offset:51008
	s_waitcnt lgkmcnt(8)
	v_pk_mul_f32 v[30:31], v[30:31], v[76:77] op_sel_hi:[1,0]
	v_pk_mul_f32 v[28:29], v[28:29], v[76:77] op_sel_hi:[1,0]
	v_pk_mul_f32 v[42:43], v[42:43], v[76:77] op_sel_hi:[1,0]
	v_pk_mul_f32 v[40:41], v[40:41], v[76:77] op_sel_hi:[1,0]
	v_pk_mul_f32 v[34:35], v[34:35], v[76:77] op_sel_hi:[1,0]
	v_pk_mul_f32 v[32:33], v[32:33], v[76:77] op_sel_hi:[1,0]
	v_pk_mul_f32 v[38:39], v[38:39], v[76:77] op_sel_hi:[1,0]
	v_pk_mul_f32 v[36:37], v[36:37], v[76:77] op_sel_hi:[1,0]
	v_pk_mul_f32 v[58:59], v[58:59], v[76:77] op_sel_hi:[1,0]
	v_pk_mul_f32 v[56:57], v[56:57], v[76:77] op_sel_hi:[1,0]
	v_pk_mul_f32 v[54:55], v[54:55], v[76:77] op_sel_hi:[1,0]
	v_pk_mul_f32 v[52:53], v[52:53], v[76:77] op_sel_hi:[1,0]
	v_pk_mul_f32 v[46:47], v[46:47], v[76:77] op_sel_hi:[1,0]
	v_pk_mul_f32 v[44:45], v[44:45], v[76:77] op_sel_hi:[1,0]
	v_pk_mul_f32 v[50:51], v[50:51], v[76:77] op_sel_hi:[1,0]
	v_pk_mul_f32 v[48:49], v[48:49], v[76:77] op_sel_hi:[1,0]
	s_waitcnt lgkmcnt(7)
	v_mfma_f32_16x16x32_bf16 v[28:31], v[88:91], v[72:75], v[28:31]
	ds_read_b128 v[88:91], v83 offset:34880
	s_waitcnt lgkmcnt(7)
	v_mfma_f32_16x16x32_bf16 v[40:43], v[92:95], v[72:75], v[40:43]
	ds_read_b128 v[92:95], v82 offset:34880
	s_waitcnt lgkmcnt(7)
	v_mfma_f32_16x16x32_bf16 v[32:35], v[96:99], v[72:75], v[32:35]
	ds_read_b128 v[96:99], v190 offset:34880
	s_waitcnt lgkmcnt(7)
	v_mfma_f32_16x16x32_bf16 v[36:39], v[100:103], v[72:75], v[36:39]
	ds_read_b128 v[100:103], v191 offset:34880
	s_waitcnt lgkmcnt(7)
	v_mfma_f32_16x16x32_bf16 v[56:59], v[104:107], v[72:75], v[56:59]
	ds_read_b128 v[104:107], v83 offset:44032
	s_waitcnt lgkmcnt(7)
	v_mfma_f32_16x16x32_bf16 v[52:55], v[194:197], v[72:75], v[52:55]
	ds_read_b128 v[194:197], v84 offset:46336
	s_waitcnt lgkmcnt(7)
	v_mfma_f32_16x16x32_bf16 v[44:47], v[198:201], v[72:75], v[44:47]
	ds_read_b128 v[198:201], v85 offset:48640
	s_waitcnt lgkmcnt(7)
	v_mfma_f32_16x16x32_bf16 v[48:51], v[232:235], v[72:75], v[48:51]
	ds_read_b128 v[232:235], v86 offset:50944
	s_waitcnt lgkmcnt(7)
	v_mfma_f32_16x16x32_bf16 v[28:31], v[88:91], v[68:71], v[28:31]
	s_waitcnt lgkmcnt(6)
	v_mfma_f32_16x16x32_bf16 v[40:43], v[92:95], v[68:71], v[40:43]
	s_waitcnt lgkmcnt(5)
	v_mfma_f32_16x16x32_bf16 v[32:35], v[96:99], v[68:71], v[32:35]
	s_waitcnt lgkmcnt(4)
	v_mfma_f32_16x16x32_bf16 v[36:39], v[100:103], v[68:71], v[36:39]
	s_waitcnt lgkmcnt(3)
	v_mfma_f32_16x16x32_bf16 v[56:59], v[104:107], v[68:71], v[56:59]
	s_waitcnt lgkmcnt(2)
	v_mfma_f32_16x16x32_bf16 v[52:55], v[194:197], v[68:71], v[52:55]
	s_waitcnt lgkmcnt(1)
	v_mfma_f32_16x16x32_bf16 v[44:47], v[198:201], v[68:71], v[44:47]
	s_waitcnt lgkmcnt(0)
	v_mfma_f32_16x16x32_bf16 v[48:51], v[232:235], v[68:71], v[48:51]
	s_waitcnt vmcnt(19)
	v_mov_b64_e32 v[74:75], v[66:67]
	v_mov_b64_e32 v[70:71], v[62:63]
	v_mov_b64_e32 v[72:73], v[64:65]
	v_mov_b64_e32 v[68:69], v[60:61]
	s_cbranch_scc0 .LBB0_1135
